# diff attention tile loop: the 7 packed f32 adds of the softmax row sum split into single adds (bit-identical)
# speedup vs baseline: 1.0052x; 1.0004x over previous
.LBB0_526:
	v_sub_f32_e32 v155, v162, v203
	v_fma_f32 v129, v161, v129, v155
	v_exp_f32_e32 v144, v129
	v_fma_f32 v129, v161, v130, v155
	v_exp_f32_e32 v130, v129
	v_fma_f32 v129, v161, v131, v155
	v_exp_f32_e32 v146, v129
	v_fma_f32 v129, v161, v132, v155
	v_exp_f32_e32 v148, v129
	v_fma_f32 v129, v161, v133, v155
	v_exp_f32_e32 v150, v129
	v_fma_f32 v129, v161, v134, v155
	v_fma_f32 v132, v161, v139, v155
	v_exp_f32_e32 v152, v129
	v_fma_f32 v129, v161, v135, v155
	v_fma_f32 v131, v161, v137, v155
	v_exp_f32_e32 v147, v132
	v_fma_f32 v132, v161, v140, v155
	v_fma_f32 v128, v161, v128, v155
	v_exp_f32_e32 v154, v129
	v_fma_f32 v129, v161, v136, v155
	v_exp_f32_e32 v145, v131
	v_fma_f32 v131, v161, v138, v155
	v_exp_f32_e32 v149, v132
	v_fma_f32 v132, v161, v141, v155
	v_exp_f32_e32 v128, v128
	v_exp_f32_e32 v129, v129
	v_exp_f32_e32 v131, v131
	v_exp_f32_e32 v151, v132
	v_fma_f32 v132, v161, v142, v155
	v_fmac_f32_e32 v155, v161, v143
	v_exp_f32_e32 v153, v132
	v_exp_f32_e32 v155, v155
	v_add_f32_e32 v132, v128, v144
	v_add_f32_e32 v133, v129, v145
	v_add_f32_e32 v134, v130, v146
	v_add_f32_e32 v135, v131, v147
	v_add_f32_e32 v136, v152, v154
	v_add_f32_e32 v137, v153, v155
	v_add_f32_e32 v132, v132, v134
	v_add_f32_e32 v133, v133, v135
	v_add_f32_e32 v134, v148, v150
	v_add_f32_e32 v135, v149, v151
	s_nop 0
	v_add_f32_e32 v134, v134, v136
	v_add_f32_e32 v135, v135, v137
	ds_read_b64_tr_b16 v[136:137], v160 offset:34816
	ds_read_b64_tr_b16 v[138:139], v160 offset:37376
	ds_read_b64_tr_b16 v[140:141], v160 offset:34880
	ds_read_b64_tr_b16 v[142:143], v160 offset:37440
	v_add_f32_e32 v132, v132, v134
	v_add_f32_e32 v133, v133, v135
	v_cvt_pk_bf16_f32 v134, v148, v150
	v_add_f32_e32 v132, v132, v133
	v_add_f32_e32 v208, v208, v132
	v_cvt_pk_bf16_f32 v132, v128, v144
	v_cvt_pk_bf16_f32 v133, v130, v146
	v_cvt_pk_bf16_f32 v135, v152, v154
	v_cvt_pk_bf16_f32 v128, v129, v145
	v_cvt_pk_bf16_f32 v129, v131, v147
	v_cvt_pk_bf16_f32 v130, v149, v151
	v_cvt_pk_bf16_f32 v131, v153, v155
	ds_read_b64_tr_b16 v[144:145], v160 offset:34944
	ds_read_b64_tr_b16 v[146:147], v160 offset:37504
	ds_read_b64_tr_b16 v[148:149], v160 offset:35008
	ds_read_b64_tr_b16 v[150:151], v160 offset:37568
	s_waitcnt lgkmcnt(6)
	v_mfma_f32_32x32x16_bf16 v[96:111], v[136:139], v[132:135], v[96:111]
	ds_read_b64_tr_b16 v[136:137], v160 offset:39936
	ds_read_b64_tr_b16 v[138:139], v160 offset:42496
	s_waitcnt lgkmcnt(6)
	v_mfma_f32_32x32x16_bf16 v[80:95], v[140:143], v[132:135], v[80:95]
	ds_read_b64_tr_b16 v[140:141], v160 offset:40000
	ds_read_b64_tr_b16 v[142:143], v160 offset:42560
	s_waitcnt lgkmcnt(6)
	v_mfma_f32_32x32x16_bf16 v[48:63], v[144:147], v[132:135], v[48:63]
	ds_read_b64_tr_b16 v[144:145], v160 offset:40064
	ds_read_b64_tr_b16 v[146:147], v160 offset:42624
	s_waitcnt lgkmcnt(6)
	v_mfma_f32_32x32x16_bf16 v[16:31], v[148:151], v[132:135], v[16:31]
	ds_read_b64_tr_b16 v[148:149], v160 offset:40128
	ds_read_b64_tr_b16 v[150:151], v160 offset:42688
	s_waitcnt lgkmcnt(6)
	v_mfma_f32_32x32x16_bf16 v[96:111], v[136:139], v[128:131], v[96:111]
	s_waitcnt lgkmcnt(4)
	v_mfma_f32_32x32x16_bf16 v[80:95], v[140:143], v[128:131], v[80:95]
	s_waitcnt lgkmcnt(2)
	v_mfma_f32_32x32x16_bf16 v[48:63], v[144:147], v[128:131], v[48:63]
	s_waitcnt lgkmcnt(0)
	v_mfma_f32_32x32x16_bf16 v[16:31], v[148:151], v[128:131], v[16:31]
